# P2 FFN weight transposition rewritten by hand: 16B loads, in-register 8x4 transposition, no LDS, double-buffered
# speedup vs baseline: 1.0316x; 1.0316x over previous
; #define LAS __attribute__((address_space(3)))
; DI unsigned pk(float a, float b) { f32x2 v = {a, b}; bf16x2_t r = __builtin_convertvector(v, bf16x2_t); return __builtin_bit_cast(unsigned, r); }
; DI void p0_transpose_item(const float* W, int K, int N, bf16_t* WT, const float* gain, bool is_win, LAS float* scr, int item, int lane) {
;     const int nblk = N / 32, kb = item / nblk, nb = item % nblk, k0 = 64 * kb, n0 = 32 * nb;
;     float cs = 1.f; int prow = n0;
;     if (is_win) { prow = win_perm(n0); if (n0 < 512) cs = 0.125f; else if (n0 >= 1280 && n0 < 1792) cs = 0.08838834764831845f; }
; #pragma unroll 8
;     for (int i = 0; i < 32; ++i) { const int kk = 2 * i + (lane >> 5); float w = __builtin_nontemporal_load(W + (size_t)(k0 + kk) * N + n0 + (lane & 31)) * cs;     if (gain) w *= gain[k0 + kk]; scr[kk * 33 + (lane & 31)] = w; }
;     asm volatile("s_waitcnt lgkmcnt(0)" ::: "memory");
;     const int c = lane & 7;
; #pragma unroll
;     for (int j = 0; j < 4; ++j) { const int n = (lane >> 3) + 8 * j; const LAS float* s = scr + (8 * c) * 33 + n;
;         u32x4 o; o.x = pk(s[0 * 33], s[1 * 33]); o.y = pk(s[2 * 33], s[3 * 33]); o.z = pk(s[4 * 33], s[5 * 33]); o.w = pk(s[6 * 33], s[7 * 33]);
;         *(u32x4*)(WT + (size_t)(prow + n) * K + k0 + 8 * c) = o; }
; DI void p2_ffn_weights(const Params& P, lds_t* lds, int GP, int bx, int wave, int lane) {
;     unsigned char* ws = P.ws;
;     LAS float* scr = (LAS float*)(lds + wave * 16384);
;     constexpr int I_UP = (DM / 64) * (FF / 32), I_DN = (FF / 64) * (DM / 32);
;     for (int it = bx * 8 + wave; it < I_UP + I_DN; it += GP * 8) {
;         if (it < I_UP) p0_transpose_item(P.w_up, DM, FF, (bf16_t*)(ws + WS_WUP), P.norm2, false, scr, it, lane);
;         else p0_transpose_item(P.w_down, FF, DM, (bf16_t*)(ws + WS_WDN), nullptr, false, scr, it - I_UP, lane);
;     }
; }
.LBB0_591:
	s_waitcnt vmcnt(0)
	v_mov_b32_e32 v8, v175
	s_cmpk_gt_i32 s64, 0xfff
	s_cbranch_scc1 .LBB0_618
	v_and_b32_e32 v109, 7, v201
	v_lshlrev_b32_e32 v108, 4, v109
	v_lshlrev_b32_e32 v111, 2, v109
	v_lshrrev_b32_e32 v109, 3, v201
	v_lshlrev_b32_e32 v110, 5, v109
	v_lshlrev_b32_e32 v112, 4, v109
	s_lshl_b32 s27, s77, 3
	s_mov_b32 s26, s64
	s_cmpk_lt_u32 s26, 0x800
	s_cbranch_scc0 .Lffn_dn_p
	s_lshr_b32 s28, s26, 7
	s_and_b32 s29, s26, 0x7f
	v_readlane_b32 s4, v255, 4
	v_readlane_b32 s5, v255, 5
	s_lshl_b32 s30, s28, 20
	s_lshl_b32 s0, s29, 7
	s_add_u32 s30, s30, s0
	s_add_u32 s4, s4, s30
	s_addc_u32 s5, s5, 0
	s_lshl_b32 s30, s29, 16
	s_lshl_b32 s0, s28, 7
	s_add_u32 s30, s30, s0
	s_add_u32 s30, s30, 0xa00000
	s_add_u32 s6, s68, s30
	s_addc_u32 s7, s69, 0
	s_movk_i32 s8, 0x4000
	s_movk_i32 s9, 0x800
	s_mov_b32 s10, 1
	s_branch .Lffn_gp_p
.Lffn_dn_p:
	s_sub_u32 s30, s26, 0x800
	s_lshr_b32 s28, s30, 5
	s_and_b32 s29, s30, 31
	v_readlane_b32 s4, v255, 6
	v_readlane_b32 s5, v255, 7
	s_lshl_b32 s30, s28, 18
	s_lshl_b32 s0, s29, 7
	s_add_u32 s30, s30, s0
	s_add_u32 s4, s4, s30
	s_addc_u32 s5, s5, 0
	s_lshl_b32 s30, s29, 18
	s_lshl_b32 s0, s28, 7
	s_add_u32 s30, s30, s0
	s_add_u32 s30, s30, 0x1200000
	s_add_u32 s6, s68, s30
	s_addc_u32 s7, s69, 0
	s_movk_i32 s8, 0x1000
	s_movk_i32 s9, 0x2000
	s_mov_b32 s10, 0
	s_and_b32 s28, s28, 15
.Lffn_gp_p:
	v_readlane_b32 s12, v255, 2
	v_readlane_b32 s13, v255, 3
	s_lshl_b32 s28, s28, 8
	s_add_u32 s12, s12, s28
	s_addc_u32 s13, s13, 0
	s_lshl_b32 s28, s8, 3
	v_mad_u32_u24 v40, v109, s28, v108
	v_add_u32_e32 v41, s8, v40
	v_add_u32_e32 v42, s8, v41
	v_add_u32_e32 v43, s8, v42
	v_add_u32_e32 v44, s8, v43
	v_add_u32_e32 v45, s8, v44
	v_add_u32_e32 v46, s8, v45
	v_add_u32_e32 v47, s8, v46
	s_nop 3
	global_load_dwordx4 v[0:3], v40, s[4:5] nt
	global_load_dwordx4 v[4:7], v41, s[4:5] nt
	global_load_dwordx4 v[8:11], v42, s[4:5] nt
	global_load_dwordx4 v[12:15], v43, s[4:5] nt
	global_load_dwordx4 v[16:19], v44, s[4:5] nt
	global_load_dwordx4 v[20:23], v45, s[4:5] nt
	global_load_dwordx4 v[24:27], v46, s[4:5] nt
	global_load_dwordx4 v[28:31], v47, s[4:5] nt
	global_load_dwordx4 v[32:35], v110, s[12:13]
	global_load_dwordx4 v[36:39], v110, s[12:13] offset:16
.Lffn_top:
	s_add_u32 s26, s26, s27
	s_cmpk_lt_u32 s26, 0x1000
	s_cbranch_scc0 .Lffn_last_a
	s_cmpk_lt_u32 s26, 0x800
	s_cbranch_scc0 .Lffn_dn_na
	s_lshr_b32 s28, s26, 7
	s_and_b32 s29, s26, 0x7f
	v_readlane_b32 s14, v255, 4
	v_readlane_b32 s15, v255, 5
	s_lshl_b32 s30, s28, 20
	s_lshl_b32 s0, s29, 7
	s_add_u32 s30, s30, s0
	s_add_u32 s14, s14, s30
	s_addc_u32 s15, s15, 0
	s_lshl_b32 s30, s29, 16
	s_lshl_b32 s0, s28, 7
	s_add_u32 s30, s30, s0
	s_add_u32 s30, s30, 0xa00000
	s_add_u32 s16, s68, s30
	s_addc_u32 s17, s69, 0
	s_movk_i32 s18, 0x4000
	s_movk_i32 s19, 0x800
	s_mov_b32 s20, 1
	s_branch .Lffn_gp_na
.Lffn_dn_na:
	s_sub_u32 s30, s26, 0x800
	s_lshr_b32 s28, s30, 5
	s_and_b32 s29, s30, 31
	v_readlane_b32 s14, v255, 6
	v_readlane_b32 s15, v255, 7
	s_lshl_b32 s30, s28, 18
	s_lshl_b32 s0, s29, 7
	s_add_u32 s30, s30, s0
	s_add_u32 s14, s14, s30
	s_addc_u32 s15, s15, 0
	s_lshl_b32 s30, s29, 18
	s_lshl_b32 s0, s28, 7
	s_add_u32 s30, s30, s0
	s_add_u32 s30, s30, 0x1200000
	s_add_u32 s16, s68, s30
	s_addc_u32 s17, s69, 0
	s_movk_i32 s18, 0x1000
	s_movk_i32 s19, 0x2000
	s_mov_b32 s20, 0
	s_and_b32 s28, s28, 15
.Lffn_gp_na:
	v_readlane_b32 s24, v255, 2
	v_readlane_b32 s25, v255, 3
	s_lshl_b32 s28, s28, 8
	s_add_u32 s24, s24, s28
	s_addc_u32 s25, s25, 0
	s_lshl_b32 s28, s18, 3
	v_mad_u32_u24 v40, v109, s28, v108
	v_add_u32_e32 v41, s18, v40
	v_add_u32_e32 v42, s18, v41
	v_add_u32_e32 v43, s18, v42
	v_add_u32_e32 v44, s18, v43
	v_add_u32_e32 v45, s18, v44
	v_add_u32_e32 v46, s18, v45
	v_add_u32_e32 v47, s18, v46
	s_nop 3
	global_load_dwordx4 v[64:67], v40, s[14:15] nt
	global_load_dwordx4 v[68:71], v41, s[14:15] nt
	global_load_dwordx4 v[72:75], v42, s[14:15] nt
	global_load_dwordx4 v[76:79], v43, s[14:15] nt
	global_load_dwordx4 v[80:83], v44, s[14:15] nt
	global_load_dwordx4 v[84:87], v45, s[14:15] nt
	global_load_dwordx4 v[88:91], v46, s[14:15] nt
	global_load_dwordx4 v[92:95], v47, s[14:15] nt
	global_load_dwordx4 v[96:99], v110, s[24:25]
	global_load_dwordx4 v[100:103], v110, s[24:25] offset:16
	s_waitcnt vmcnt(10)
	v_mad_u32_u24 v48, v111, s9, v112
	v_add_u32_e32 v49, s9, v48
	v_add_u32_e32 v50, s9, v49
	v_add_u32_e32 v51, s9, v50
	s_cmp_eq_u32 s10, 0
	s_cbranch_scc1 .Lffn_nog_ma
	v_mul_f32_e32 v0, v0, v32
	v_mul_f32_e32 v1, v1, v32
	v_mul_f32_e32 v2, v2, v32
	v_mul_f32_e32 v3, v3, v32
	v_mul_f32_e32 v4, v4, v33
	v_mul_f32_e32 v5, v5, v33
	v_mul_f32_e32 v6, v6, v33
	v_mul_f32_e32 v7, v7, v33
	v_mul_f32_e32 v8, v8, v34
	v_mul_f32_e32 v9, v9, v34
	v_mul_f32_e32 v10, v10, v34
	v_mul_f32_e32 v11, v11, v34
	v_mul_f32_e32 v12, v12, v35
	v_mul_f32_e32 v13, v13, v35
	v_mul_f32_e32 v14, v14, v35
	v_mul_f32_e32 v15, v15, v35
	v_mul_f32_e32 v16, v16, v36
	v_mul_f32_e32 v17, v17, v36
	v_mul_f32_e32 v18, v18, v36
	v_mul_f32_e32 v19, v19, v36
	v_mul_f32_e32 v20, v20, v37
	v_mul_f32_e32 v21, v21, v37
	v_mul_f32_e32 v22, v22, v37
	v_mul_f32_e32 v23, v23, v37
	v_mul_f32_e32 v24, v24, v38
	v_mul_f32_e32 v25, v25, v38
	v_mul_f32_e32 v26, v26, v38
	v_mul_f32_e32 v27, v27, v38
	v_mul_f32_e32 v28, v28, v39
	v_mul_f32_e32 v29, v29, v39
	v_mul_f32_e32 v30, v30, v39
	v_mul_f32_e32 v31, v31, v39
.Lffn_nog_ma:
	v_cvt_pk_bf16_f32 v52, v0, v4
	v_cvt_pk_bf16_f32 v53, v8, v12
	v_cvt_pk_bf16_f32 v54, v16, v20
	v_cvt_pk_bf16_f32 v55, v24, v28
	global_store_dwordx4 v48, v[52:55], s[6:7]
	v_cvt_pk_bf16_f32 v56, v1, v5
	v_cvt_pk_bf16_f32 v57, v9, v13
	v_cvt_pk_bf16_f32 v58, v17, v21
	v_cvt_pk_bf16_f32 v59, v25, v29
	global_store_dwordx4 v49, v[56:59], s[6:7]
	v_cvt_pk_bf16_f32 v60, v2, v6
	v_cvt_pk_bf16_f32 v61, v10, v14
	v_cvt_pk_bf16_f32 v62, v18, v22
	v_cvt_pk_bf16_f32 v63, v26, v30
	global_store_dwordx4 v50, v[60:63], s[6:7]
	v_cvt_pk_bf16_f32 v104, v3, v7
	v_cvt_pk_bf16_f32 v105, v11, v15
	v_cvt_pk_bf16_f32 v106, v19, v23
	v_cvt_pk_bf16_f32 v107, v27, v31
	global_store_dwordx4 v51, v[104:107], s[6:7]
	s_add_u32 s26, s26, s27
	s_cmpk_lt_u32 s26, 0x1000
	s_cbranch_scc0 .Lffn_last_b
	s_cmpk_lt_u32 s26, 0x800
	s_cbranch_scc0 .Lffn_dn_nb
	s_lshr_b32 s28, s26, 7
	s_and_b32 s29, s26, 0x7f
	v_readlane_b32 s4, v255, 4
	v_readlane_b32 s5, v255, 5
	s_lshl_b32 s30, s28, 20
	s_lshl_b32 s0, s29, 7
	s_add_u32 s30, s30, s0
	s_add_u32 s4, s4, s30
	s_addc_u32 s5, s5, 0
	s_lshl_b32 s30, s29, 16
	s_lshl_b32 s0, s28, 7
	s_add_u32 s30, s30, s0
	s_add_u32 s30, s30, 0xa00000
	s_add_u32 s6, s68, s30
	s_addc_u32 s7, s69, 0
	s_movk_i32 s8, 0x4000
	s_movk_i32 s9, 0x800
	s_mov_b32 s10, 1
	s_branch .Lffn_gp_nb

; #define LAS __attribute__((address_space(3)))
; DI unsigned pk(float a, float b) { f32x2 v = {a, b}; bf16x2_t r = __builtin_convertvector(v, bf16x2_t); return __builtin_bit_cast(unsigned, r); }
; DI void p0_transpose_item(const float* W, int K, int N, bf16_t* WT, const float* gain, bool is_win, LAS float* scr, int item, int lane) {
;     const int nblk = N / 32, kb = item / nblk, nb = item % nblk, k0 = 64 * kb, n0 = 32 * nb;
;     float cs = 1.f; int prow = n0;
;     if (is_win) { prow = win_perm(n0); if (n0 < 512) cs = 0.125f; else if (n0 >= 1280 && n0 < 1792) cs = 0.08838834764831845f; }
; #pragma unroll 8
;     for (int i = 0; i < 32; ++i) { const int kk = 2 * i + (lane >> 5); float w = __builtin_nontemporal_load(W + (size_t)(k0 + kk) * N + n0 + (lane & 31)) * cs;     if (gain) w *= gain[k0 + kk]; scr[kk * 33 + (lane & 31)] = w; }
;     asm volatile("s_waitcnt lgkmcnt(0)" ::: "memory");
;     const int c = lane & 7;
; #pragma unroll
;     for (int j = 0; j < 4; ++j) { const int n = (lane >> 3) + 8 * j; const LAS float* s = scr + (8 * c) * 33 + n;
;         u32x4 o; o.x = pk(s[0 * 33], s[1 * 33]); o.y = pk(s[2 * 33], s[3 * 33]); o.z = pk(s[4 * 33], s[5 * 33]); o.w = pk(s[6 * 33], s[7 * 33]);
;         *(u32x4*)(WT + (size_t)(prow + n) * K + k0 + 8 * c) = o; }
.Lffn_gp_nb:
	v_readlane_b32 s12, v255, 2
	v_readlane_b32 s13, v255, 3
	s_lshl_b32 s28, s28, 8
	s_add_u32 s12, s12, s28
	s_addc_u32 s13, s13, 0
	s_lshl_b32 s28, s8, 3
	v_mad_u32_u24 v40, v109, s28, v108
	v_add_u32_e32 v41, s8, v40
	v_add_u32_e32 v42, s8, v41
	v_add_u32_e32 v43, s8, v42
	v_add_u32_e32 v44, s8, v43
	v_add_u32_e32 v45, s8, v44
	v_add_u32_e32 v46, s8, v45
	v_add_u32_e32 v47, s8, v46
	s_nop 3
	global_load_dwordx4 v[0:3], v40, s[4:5] nt
	global_load_dwordx4 v[4:7], v41, s[4:5] nt
	global_load_dwordx4 v[8:11], v42, s[4:5] nt
	global_load_dwordx4 v[12:15], v43, s[4:5] nt
	global_load_dwordx4 v[16:19], v44, s[4:5] nt
	global_load_dwordx4 v[20:23], v45, s[4:5] nt
	global_load_dwordx4 v[24:27], v46, s[4:5] nt
	global_load_dwordx4 v[28:31], v47, s[4:5] nt
	global_load_dwordx4 v[32:35], v110, s[12:13]
	global_load_dwordx4 v[36:39], v110, s[12:13] offset:16
	s_waitcnt vmcnt(10)
	v_mad_u32_u24 v48, v111, s19, v112
	v_add_u32_e32 v49, s19, v48
	v_add_u32_e32 v50, s19, v49
	v_add_u32_e32 v51, s19, v50
	s_cmp_eq_u32 s20, 0
	s_cbranch_scc1 .Lffn_nog_mb
	v_mul_f32_e32 v64, v64, v96
	v_mul_f32_e32 v65, v65, v96
	v_mul_f32_e32 v66, v66, v96
	v_mul_f32_e32 v67, v67, v96
	v_mul_f32_e32 v68, v68, v97
	v_mul_f32_e32 v69, v69, v97
	v_mul_f32_e32 v70, v70, v97
	v_mul_f32_e32 v71, v71, v97
	v_mul_f32_e32 v72, v72, v98
	v_mul_f32_e32 v73, v73, v98
	v_mul_f32_e32 v74, v74, v98
	v_mul_f32_e32 v75, v75, v98
	v_mul_f32_e32 v76, v76, v99
	v_mul_f32_e32 v77, v77, v99
	v_mul_f32_e32 v78, v78, v99
	v_mul_f32_e32 v79, v79, v99
	v_mul_f32_e32 v80, v80, v100
	v_mul_f32_e32 v81, v81, v100
	v_mul_f32_e32 v82, v82, v100
	v_mul_f32_e32 v83, v83, v100
	v_mul_f32_e32 v84, v84, v101
	v_mul_f32_e32 v85, v85, v101
	v_mul_f32_e32 v86, v86, v101
	v_mul_f32_e32 v87, v87, v101
	v_mul_f32_e32 v88, v88, v102
	v_mul_f32_e32 v89, v89, v102
	v_mul_f32_e32 v90, v90, v102
	v_mul_f32_e32 v91, v91, v102
	v_mul_f32_e32 v92, v92, v103
	v_mul_f32_e32 v93, v93, v103
	v_mul_f32_e32 v94, v94, v103
	v_mul_f32_e32 v95, v95, v103
.Lffn_nog_mb:
	v_cvt_pk_bf16_f32 v52, v64, v68
	v_cvt_pk_bf16_f32 v53, v72, v76
	v_cvt_pk_bf16_f32 v54, v80, v84
	v_cvt_pk_bf16_f32 v55, v88, v92
	global_store_dwordx4 v48, v[52:55], s[16:17]
	v_cvt_pk_bf16_f32 v56, v65, v69
	v_cvt_pk_bf16_f32 v57, v73, v77
	v_cvt_pk_bf16_f32 v58, v81, v85
	v_cvt_pk_bf16_f32 v59, v89, v93
	global_store_dwordx4 v49, v[56:59], s[16:17]
	v_cvt_pk_bf16_f32 v60, v66, v70
	v_cvt_pk_bf16_f32 v61, v74, v78
	v_cvt_pk_bf16_f32 v62, v82, v86
	v_cvt_pk_bf16_f32 v63, v90, v94
	global_store_dwordx4 v50, v[60:63], s[16:17]
	v_cvt_pk_bf16_f32 v104, v67, v71
	v_cvt_pk_bf16_f32 v105, v75, v79
	v_cvt_pk_bf16_f32 v106, v83, v87
	v_cvt_pk_bf16_f32 v107, v91, v95
	global_store_dwordx4 v51, v[104:107], s[16:17]
	s_branch .Lffn_top
.Lffn_last_a:
	s_waitcnt vmcnt(0)
	v_mad_u32_u24 v48, v111, s9, v112
	v_add_u32_e32 v49, s9, v48
	v_add_u32_e32 v50, s9, v49
	v_add_u32_e32 v51, s9, v50
	s_cmp_eq_u32 s10, 0
	s_cbranch_scc1 .Lffn_nog_la
	v_mul_f32_e32 v0, v0, v32
	v_mul_f32_e32 v1, v1, v32
	v_mul_f32_e32 v2, v2, v32
	v_mul_f32_e32 v3, v3, v32
	v_mul_f32_e32 v4, v4, v33
	v_mul_f32_e32 v5, v5, v33
	v_mul_f32_e32 v6, v6, v33
	v_mul_f32_e32 v7, v7, v33
	v_mul_f32_e32 v8, v8, v34
	v_mul_f32_e32 v9, v9, v34
	v_mul_f32_e32 v10, v10, v34
	v_mul_f32_e32 v11, v11, v34
	v_mul_f32_e32 v12, v12, v35
	v_mul_f32_e32 v13, v13, v35
	v_mul_f32_e32 v14, v14, v35
	v_mul_f32_e32 v15, v15, v35
	v_mul_f32_e32 v16, v16, v36
	v_mul_f32_e32 v17, v17, v36
	v_mul_f32_e32 v18, v18, v36
	v_mul_f32_e32 v19, v19, v36
	v_mul_f32_e32 v20, v20, v37
	v_mul_f32_e32 v21, v21, v37
	v_mul_f32_e32 v22, v22, v37
	v_mul_f32_e32 v23, v23, v37
	v_mul_f32_e32 v24, v24, v38
	v_mul_f32_e32 v25, v25, v38
	v_mul_f32_e32 v26, v26, v38
	v_mul_f32_e32 v27, v27, v38
	v_mul_f32_e32 v28, v28, v39
	v_mul_f32_e32 v29, v29, v39
	v_mul_f32_e32 v30, v30, v39
	v_mul_f32_e32 v31, v31, v39
; #define LAS __attribute__((address_space(3)))
; DI int lane_id() { return (int)__builtin_amdgcn_mbcnt_hi(~0u, __builtin_amdgcn_mbcnt_lo(~0u, 0u)); }
; DI unsigned pk(float a, float b) { f32x2 v = {a, b}; bf16x2_t r = __builtin_convertvector(v, bf16x2_t); return __builtin_bit_cast(unsigned, r); }
; __device__ __forceinline__ void xcd_barrier(const XcdBarrier& b) {
;     asm volatile("s_waitcnt vmcnt(0)" ::: "memory");
;     __syncthreads();
;     if (b.w0 == 0 && lane_id() == 0) {
;         unsigned* bar = b.bar;
;         __builtin_amdgcn_s_waitcnt(0);
;         unsigned nloc = b.st[0], nx = b.st[1];
;         if (nloc == 0u) { xcd_barrier_complete(bar, b.x, nloc, nx); b.st[0] = nloc; b.st[1] = nx; }
; DI void p0_transpose_item(const float* W, int K, int N, bf16_t* WT, const float* gain, bool is_win, LAS float* scr, int item, int lane) {
;     const int nblk = N / 32, kb = item / nblk, nb = item % nblk, k0 = 64 * kb, n0 = 32 * nb;
;     float cs = 1.f; int prow = n0;
;     if (is_win) { prow = win_perm(n0); if (n0 < 512) cs = 0.125f; else if (n0 >= 1280 && n0 < 1792) cs = 0.08838834764831845f; }
; #pragma unroll 8
;     for (int i = 0; i < 32; ++i) { const int kk = 2 * i + (lane >> 5); float w = __builtin_nontemporal_load(W + (size_t)(k0 + kk) * N + n0 + (lane & 31)) * cs;     if (gain) w *= gain[k0 + kk]; scr[kk * 33 + (lane & 31)] = w; }
;     asm volatile("s_waitcnt lgkmcnt(0)" ::: "memory");
;     const int c = lane & 7;
; #pragma unroll
;     for (int j = 0; j < 4; ++j) { const int n = (lane >> 3) + 8 * j; const LAS float* s = scr + (8 * c) * 33 + n;
;         u32x4 o; o.x = pk(s[0 * 33], s[1 * 33]); o.y = pk(s[2 * 33], s[3 * 33]); o.z = pk(s[4 * 33], s[5 * 33]); o.w = pk(s[6 * 33], s[7 * 33]);
;         *(u32x4*)(WT + (size_t)(prow + n) * K + k0 + 8 * c) = o; }
.Lffn_nog_la:
	v_cvt_pk_bf16_f32 v52, v0, v4
	v_cvt_pk_bf16_f32 v53, v8, v12
	v_cvt_pk_bf16_f32 v54, v16, v20
	v_cvt_pk_bf16_f32 v55, v24, v28
	global_store_dwordx4 v48, v[52:55], s[6:7]
	v_cvt_pk_bf16_f32 v56, v1, v5
	v_cvt_pk_bf16_f32 v57, v9, v13
	v_cvt_pk_bf16_f32 v58, v17, v21
	v_cvt_pk_bf16_f32 v59, v25, v29
	global_store_dwordx4 v49, v[56:59], s[6:7]
	v_cvt_pk_bf16_f32 v60, v2, v6
	v_cvt_pk_bf16_f32 v61, v10, v14
	v_cvt_pk_bf16_f32 v62, v18, v22
	v_cvt_pk_bf16_f32 v63, v26, v30
	global_store_dwordx4 v50, v[60:63], s[6:7]
	v_cvt_pk_bf16_f32 v104, v3, v7
	v_cvt_pk_bf16_f32 v105, v11, v15
	v_cvt_pk_bf16_f32 v106, v19, v23
	v_cvt_pk_bf16_f32 v107, v27, v31
	global_store_dwordx4 v51, v[104:107], s[6:7]
	s_branch .Lffn_done
.Lffn_last_b:
	s_waitcnt vmcnt(0)
	v_mad_u32_u24 v48, v111, s19, v112
	v_add_u32_e32 v49, s19, v48
	v_add_u32_e32 v50, s19, v49
	v_add_u32_e32 v51, s19, v50
	s_cmp_eq_u32 s20, 0
	s_cbranch_scc1 .Lffn_nog_lb
	v_mul_f32_e32 v64, v64, v96
	v_mul_f32_e32 v65, v65, v96
	v_mul_f32_e32 v66, v66, v96
	v_mul_f32_e32 v67, v67, v96
	v_mul_f32_e32 v68, v68, v97
	v_mul_f32_e32 v69, v69, v97
	v_mul_f32_e32 v70, v70, v97
	v_mul_f32_e32 v71, v71, v97
	v_mul_f32_e32 v72, v72, v98
	v_mul_f32_e32 v73, v73, v98
	v_mul_f32_e32 v74, v74, v98
	v_mul_f32_e32 v75, v75, v98
	v_mul_f32_e32 v76, v76, v99
	v_mul_f32_e32 v77, v77, v99
	v_mul_f32_e32 v78, v78, v99
	v_mul_f32_e32 v79, v79, v99
	v_mul_f32_e32 v80, v80, v100
	v_mul_f32_e32 v81, v81, v100
	v_mul_f32_e32 v82, v82, v100
	v_mul_f32_e32 v83, v83, v100
	v_mul_f32_e32 v84, v84, v101
	v_mul_f32_e32 v85, v85, v101
	v_mul_f32_e32 v86, v86, v101
	v_mul_f32_e32 v87, v87, v101
	v_mul_f32_e32 v88, v88, v102
	v_mul_f32_e32 v89, v89, v102
	v_mul_f32_e32 v90, v90, v102
	v_mul_f32_e32 v91, v91, v102
	v_mul_f32_e32 v92, v92, v103
	v_mul_f32_e32 v93, v93, v103
	v_mul_f32_e32 v94, v94, v103
	v_mul_f32_e32 v95, v95, v103
.Lffn_nog_lb:
	v_cvt_pk_bf16_f32 v52, v64, v68
	v_cvt_pk_bf16_f32 v53, v72, v76
	v_cvt_pk_bf16_f32 v54, v80, v84
	v_cvt_pk_bf16_f32 v55, v88, v92
	global_store_dwordx4 v48, v[52:55], s[16:17]
	v_cvt_pk_bf16_f32 v56, v65, v69
	v_cvt_pk_bf16_f32 v57, v73, v77
	v_cvt_pk_bf16_f32 v58, v81, v85
	v_cvt_pk_bf16_f32 v59, v89, v93
	global_store_dwordx4 v49, v[56:59], s[16:17]
	v_cvt_pk_bf16_f32 v60, v66, v70
	v_cvt_pk_bf16_f32 v61, v74, v78
	v_cvt_pk_bf16_f32 v62, v82, v86
	v_cvt_pk_bf16_f32 v63, v90, v94
	global_store_dwordx4 v50, v[60:63], s[16:17]
	v_cvt_pk_bf16_f32 v104, v67, v71
	v_cvt_pk_bf16_f32 v105, v75, v79
	v_cvt_pk_bf16_f32 v106, v83, v87
	v_cvt_pk_bf16_f32 v107, v91, v95
	global_store_dwordx4 v51, v[104:107], s[16:17]
.Lffn_done:
.LBB0_618:
	s_waitcnt vmcnt(0)
	s_waitcnt vmcnt(0) lgkmcnt(0)
	s_barrier
	s_mov_b64 s[0:1], exec
	v_readlane_b32 s4, v255, 15
	v_readlane_b32 s5, v255, 16
	s_and_b64 s[4:5], s[0:1], s[4:5]
	s_mov_b64 exec, s[4:5]
	s_cbranch_execz .LBB0_670
	s_add_i32 s3, 0, 0x20200
	v_mov_b32_e32 v0, s3
	s_waitcnt vmcnt(0) expcnt(0) lgkmcnt(0)
	ds_read_b32 v2, v0
	s_add_i32 s3, 0, 0x20204
	v_mov_b32_e32 v0, s3
	ds_read_b32 v0, v0
	s_waitcnt lgkmcnt(1)
	v_cmp_ne_u32_e32 vcc, 0, v2
	s_cbranch_vccnz .LBB0_634
	v_readlane_b32 s4, v255, 8
	v_readlane_b32 s5, v255, 9
	s_load_dwordx2 s[8:9], s[4:5], 0x4
	s_add_u32 s4, s68, 0x80200
	s_addc_u32 s5, s69, 0
	s_add_u32 s6, s68, 0x80400
	s_addc_u32 s7, s69, 0
	s_waitcnt lgkmcnt(0)
	s_mul_i32 s3, s8, s96
	s_add_u32 s8, s68, 0x80500
	s_mul_i32 s3, s3, s9
	s_addc_u32 s9, s69, 0
	s_add_u32 s10, s68, 0x80600
	s_addc_u32 s11, s69, 0
	s_add_u32 s12, s68, 0x80700
	s_addc_u32 s13, s69, 0
	s_add_u32 s14, s68, 0x80800
	s_addc_u32 s15, s69, 0
	s_add_u32 s16, s68, 0x80900
	s_addc_u32 s17, s69, 0
	s_add_u32 s18, s68, 0x80a00
	s_addc_u32 s19, s69, 0
	s_add_u32 s20, s68, 0x80b00
	s_addc_u32 s21, s69, 0
	s_add_u32 s22, s68, 0x80c00
	s_addc_u32 s23, s69, 0
	s_add_u32 s24, s68, 0x80d00
	s_addc_u32 s25, s69, 0
	s_add_u32 s26, s68, 0x80e00
	s_addc_u32 s27, s69, 0
	s_add_u32 s28, s68, 0x80f00
	s_addc_u32 s29, s69, 0
	s_add_u32 s30, s68, 0x81000
	s_addc_u32 s31, s69, 0
	s_add_u32 s34, s68, 0x81100
	s_addc_u32 s35, s69, 0
	s_add_u32 s36, s68, 0x81200
	s_addc_u32 s37, s69, 0
	s_add_u32 s38, s68, 0x81300
	s_addc_u32 s39, s69, 0
	s_mov_b32 s46, 1
	v_mov_b32_e32 v16, 0
	s_branch .LBB0_622
